# w2 GEMMs (K=8192): tile order transposed inside each 8x8 group so a round covers 4 row tiles x 8 column tiles: each HID row tile is streamed once per XCD instead of twice
# speedup vs baseline: 1.0093x; 1.0093x over previous
;   __device__ bool next(int i, Unit& u) const {
;     const long L = (long)i * G + c; if (L >= nwg) return false;
;     int wgid = (int)L; { const int q = nwg / NXCD, r = nwg % NXCD, xcd = wgid % NXCD, off = wgid / NXCD; wgid = (xcd < r ? xcd * (q + 1) : r * (q + 1) + (xcd - r) * q) + off; }
;     const int nig = WGM * nN, gid = wgid / nig, fm = gid * WGM, gsz = (nM - fm) < WGM ? (nM - fm) : WGM;
;     u.pm = fm + ((wgid % nig) % gsz); u.pn = (wgid % nig) / gsz; u.kb = 0; u.kr = (kmode == 2) ? ((i & 1) ^ 1) : kmode; return true;
; template <class Epi, class Sched, bool ALIGN_EPI = true>
; __device__ __forceinline__ void gemm_phase(LAS unsigned char* lds, const Gemm g, const Sched& S, const Epi& E) {
;   const int tid = otid(), wid = __builtin_amdgcn_readfirstlane(tid >> 6), lane = tid & 63, wr = wid >> 2, wc = wid & 3, fr = lane & 15, fq = lane >> 4;
;   const int K = g.K, nt = K / BK;
;   unsigned voffA[2], voffB[2];
; #pragma unroll
;   for (int i = 0; i < 2; ++i) { int R, C; stage_rc(tid * 16 + i * 8192, R, C); const int Rb = Epi::PERM ? ((R & ~31) + perm32(R & 31)) : R;
;     voffA[i] = (unsigned)(R * g.lda + C) * 2u; voffB[i] = (unsigned)(Rb * g.ldb + C) * 2u; }
;   const size_t koffL = (size_t)(nt - 1) * (BK * 2);
;   const size_t hstepA = (size_t)HALF * g.lda * 2, hstepB = (size_t)HALF * g.ldb * 2;
;   const size_t tstepA = 2 * hstepA, tstepB = 2 * hstepB;
;   const unsigned ldsw = (unsigned)wid * 1024u;
;   const int aoff = lds_byte(wr * 64 + fr, fq * 8), boff = lds_byte(wc * 32 + fr, fq * 8);
;     ...
;   Unit cur, nxt; int ui = 0;
;   if (!S.next(0, cur)) return;
;   f32x4 acc[2][2][4][2];
; #pragma unroll
;   for (int a = 0; a < 2; ++a)
; #pragma unroll
;     for (int b = 0; b < 2; ++b)
; #pragma unroll
;       for (int m = 0; m < 4; ++m)
; #pragma unroll
;         for (int n = 0; n < 2; ++n) acc[a][b][m][n] = (f32x4){0.f, 0.f, 0.f, 0.f};
;   bf16x8 At[4][2], B0[2][2], B1[2][2];
;   ptrdiff_t kstep = cur.kr ? -(ptrdiff_t)(BK * 2) : (ptrdiff_t)(BK * 2);
;   const char* cA = (const char*)g.A + (size_t)cur.pm * tstepA + cur.kb + (cur.kr ? koffL : 0); const char* cB = (const char*)g.Bt + (size_t)cur.pn * tstepB + cur.kb + (cur.kr ? koffL : 0);
;   PG8_STAGE(PG8_SB(0, 0), cB, voffB); PG8_STAGE(PG8_SB(0, 1), cB + hstepB, voffB); PG8_STAGE(PG8_SA(0, 0), cA, voffA); PG8_STAGE(PG8_SA(0, 1), cA + hstepA, voffA);
;   if (wr == 1) PG8_BAR;
.LBB0_957:
	v_bfe_i32 v2, v0, 27, 1
	v_lshlrev_b32_e32 v4, 4, v0
	v_lshrrev_b32_e32 v2, 22, v2
	v_add_u32_e32 v2, v4, v2
	v_and_b32_e32 v2, 0xfffffc00, v2
	v_sub_u32_e32 v2, v4, v2
	v_lshrrev_b32_e32 v3, 4, v2
	v_bitop3_b32 v3, v3, v2, 32 bitop3:0x6c
	v_ashrrev_i32_e32 v2, 31, v2
	v_lshrrev_b32_e32 v2, 26, v2
	v_ashrrev_i32_e32 v1, 31, v0
	v_add_u32_e32 v2, v3, v2
	v_lshrrev_b32_e32 v1, 26, v1
	v_ashrrev_i32_e32 v2, 6, v2
	v_add_u32_e32 v1, v0, v1
	v_mul_i32_i24_e32 v7, 64, v2
	v_ashrrev_i32_e32 v1, 6, v1
	v_sub_u32_e32 v3, v3, v7
	v_mov_b32_e32 v7, 1
	v_lshlrev_b32_e32 v5, 3, v1
	v_lshlrev_b32_e32 v6, 5, v1
	v_ashrrev_i16_sdwa v3, v7, sext(v3) dst_sel:DWORD dst_unused:UNUSED_PAD src0_sel:DWORD src1_sel:BYTE_0
	v_and_b32_e32 v5, -16, v5
	v_and_b32_e32 v6, 32, v6
	v_bfe_i32 v3, v3, 0, 16
	s_ashr_i32 s6, s3, 3
	v_add_u32_e32 v5, v2, v5
	v_and_b32_e32 v10, 3, v2
	s_mov_b32 s3, 0x3ffe0
	v_add_lshl_u32 v6, v6, v3, 1
	v_lshlrev_b32_e32 v8, 1, v5
	v_lshrrev_b32_e32 v9, 2, v5
	v_and_or_b32 v10, v5, s3, v10
	v_lshl_add_u32 v144, v5, 14, v6
	v_add_u32_e32 v5, 0x2000, v4
	s_add_i32 s6, s16, s6
	v_ashrrev_i32_e32 v4, 31, v5
	s_ashr_i32 s16, s6, 31
	v_lshrrev_b32_e32 v4, 22, v4
	s_lshr_b32 s16, s16, 26
	v_and_b32_e32 v8, 24, v8
	v_and_b32_e32 v9, 4, v9
	v_add_u32_e32 v4, v5, v4
	s_add_i32 s16, s6, s16
	v_or3_b32 v8, v10, v9, v8
	v_ashrrev_i32_e32 v4, 10, v4
	s_ashr_i32 s17, s16, 6
	s_andn2_b32 s16, s16, 63
	v_lshl_add_u32 v146, v8, 14, v6
	v_mul_i32_i24_e32 v6, 0x400, v4
	s_sub_i32 s16, s6, s16
	v_sub_u32_e32 v5, v5, v6
	s_bfe_i32 s6, s16, 0x80000
	v_lshrrev_b32_e32 v6, 4, v5
	s_bfe_u32 s6, s6, 0x3000c
	v_bitop3_b32 v6, v6, v5, 32 bitop3:0x6c
	v_lshlrev_b32_e32 v5, 3, v4
	s_add_i32 s18, s16, s6
	v_and_b32_e32 v8, -16, v5
	v_ashrrev_i32_e32 v5, 31, v6
	s_bfe_i32 s6, s18, 0x80000
	s_and_b32 s18, s18, 0xf8
	v_lshrrev_b32_e32 v5, 26, v5
	s_sub_i32 s16, s16, s18
	v_add_u32_e32 v9, v6, v5
	s_lshl_b32 s17, s17, 3
	s_sext_i32_i16 s6, s6
	s_sext_i32_i8 s16, s16
	s_ashr_i32 s7, s8, 6
	v_ashrrev_i32_e32 v5, 6, v9
	s_lshr_b32 s6, s6, 3
	s_add_i32 s36, s17, s6
	s_mov_b32 s6, s16
	v_add_u32_e32 v8, v5, v8
	v_and_b32_e32 v11, 3, v5
	s_ashr_i32 s37, s36, 31
	s_bfe_i64 s[18:19], s[6:7], 0x100000
	v_and_or_b32 v11, v8, s3, v11
	s_ashr_i32 s9, s8, 8
	s_lshl_b32 s3, s7, 10
	s_lshl_b64 s[16:17], s[36:37], 22
	s_lshl_b64 s[18:19], s[18:19], 22
	s_add_u32 s18, s0, s18
	s_addc_u32 s19, s1, s19
	s_add_u32 s42, s18, 0x3f80
	v_and_b32_e32 v9, 0xc0, v9
	s_addc_u32 s43, s19, 0
	s_add_i32 s33, s3, 0
	v_sub_u32_e32 v6, v6, v9
	s_add_i32 m0, s33, 0x10000
	v_lshlrev_b32_e32 v10, 5, v4
	v_ashrrev_i16_sdwa v6, v7, sext(v6) dst_sel:DWORD dst_unused:UNUSED_PAD src0_sel:DWORD src1_sel:BYTE_0
	v_lshlrev_b32_e32 v7, 1, v8
	v_lshrrev_b32_e32 v9, 2, v8
	global_load_lds_dwordx4 v146, s[42:43]
	s_add_i32 m0, s33, 0x12000
	v_and_b32_e32 v10, 32, v10
	v_bfe_i32 v6, v6, 0, 16
	v_and_b32_e32 v7, 24, v7
	v_and_b32_e32 v9, 4, v9
	s_add_u32 s20, s92, s16
	v_or3_b32 v7, v11, v9, v7
	v_add_lshl_u32 v9, v10, v6, 1
	s_addc_u32 s21, s93, s17
	v_lshl_add_u32 v150, v7, 14, v9
	s_add_u32 s16, s18, 0x203f80
	global_load_lds_dwordx4 v150, s[42:43]
	s_addc_u32 s17, s19, 0
	s_add_i32 m0, s33, 0x14000
	v_lshl_add_u32 v148, v8, 14, v9
	global_load_lds_dwordx4 v146, s[16:17]
	s_add_i32 m0, s33, 0x16000
	s_add_u32 s44, s20, 0x3f80
	s_addc_u32 s45, s21, 0
	s_add_i32 s37, s33, 0x2000
	global_load_lds_dwordx4 v150, s[16:17]
	s_mov_b32 m0, s33
	s_add_u32 s16, s20, 0x203f80
	global_load_lds_dwordx4 v144, s[44:45]
	s_mov_b32 m0, s37
	s_addc_u32 s17, s21, 0
	s_add_i32 s52, s33, 0x4000
	global_load_lds_dwordx4 v148, s[44:45]
	s_mov_b32 m0, s52
	s_add_i32 s53, s33, 0x6000
	global_load_lds_dwordx4 v144, s[16:17]
	s_mov_b32 m0, s53
	v_mov_b32_e32 v147, 0
	global_load_lds_dwordx4 v148, s[16:17]
	s_cmp_eq_u32 s9, 1
	s_mov_b32 s54, 0
	v_mov_b32_e32 v151, v147
	v_mov_b32_e32 v145, v147
	s_cselect_b64 s[16:17], -1, 0
	s_cmp_lg_u32 s9, 1
	v_mov_b32_e32 v149, v147
	s_cbranch_scc1 .LBB0_959
	s_barrier

;   __device__ bool next(int i, Unit& u) const {
;     const long L = (long)i * G + c; if (L >= nwg) return false;
;     int wgid = (int)L; { const int q = nwg / NXCD, r = nwg % NXCD, xcd = wgid % NXCD, off = wgid / NXCD; wgid = (xcd < r ? xcd * (q + 1) : r * (q + 1) + (xcd - r) * q) + off; }
;     const int nig = WGM * nN, gid = wgid / nig, fm = gid * WGM, gsz = (nM - fm) < WGM ? (nM - fm) : WGM;
;     u.pm = fm + ((wgid % nig) % gsz); u.pn = (wgid % nig) / gsz; u.kb = 0; u.kr = (kmode == 2) ? ((i & 1) ^ 1) : kmode; return true;
.LBB0_967:
	s_ashr_i32 s6, s22, 3
	s_add_i32 s6, s24, s6
	s_ashr_i32 s7, s6, 31
	s_lshr_b32 s7, s7, 26
	s_add_i32 s7, s6, s7
	s_ashr_i32 s22, s7, 6
	s_lshl_b32 s23, s22, 3
	s_sub_i32 s22, 64, s23
	s_min_i32 s24, s22, 8
	s_abs_i32 s22, s24
	v_cvt_f32_u32_e32 v0, s22
	s_sub_i32 s26, 0, s22
	s_andn2_b32 s7, s7, 63
	s_sub_i32 s6, s6, s7
	v_rcp_iflag_f32_e32 v0, v0
	s_abs_i32 s7, s6
	s_xor_b32 s25, s6, s24
	s_ashr_i32 s25, s25, 31
	v_mul_f32_e32 v0, 0x4f7ffffe, v0
	v_cvt_u32_f32_e32 v0, v0
	s_nop 0
	v_readfirstlane_b32 s27, v0
	s_mul_i32 s26, s26, s27
	s_mul_hi_u32 s26, s27, s26
	s_add_i32 s27, s27, s26
	s_mul_hi_u32 s26, s7, s27
	s_mul_i32 s27, s26, s22
	s_sub_i32 s7, s7, s27
	s_add_i32 s30, s26, 1
	s_sub_i32 s27, s7, s22
	s_cmp_ge_u32 s7, s22
	s_cselect_b32 s26, s30, s26
	s_cselect_b32 s7, s27, s7
	s_add_i32 s27, s26, 1
	s_cmp_ge_u32 s7, s22
	s_cselect_b32 s7, s27, s26
	s_xor_b32 s7, s7, s25
	s_sub_i32 s22, s7, s25
	s_mul_i32 s7, s22, s24
	s_sub_i32 s6, s6, s7
	s_add_i32 s24, s23, s22
	s_mov_b32 s22, s6
	s_andn2_b32 s65, 1, s54

;   __device__ bool next(int i, Unit& u) const {
;     const long L = (long)i * G + c; if (L >= nwg) return false;
;     int wgid = (int)L; { const int q = nwg / NXCD, r = nwg % NXCD, xcd = wgid % NXCD, off = wgid / NXCD; wgid = (xcd < r ? xcd * (q + 1) : r * (q + 1) + (xcd - r) * q) + off; }
;     const int nig = WGM * nN, gid = wgid / nig, fm = gid * WGM, gsz = (nM - fm) < WGM ? (nM - fm) : WGM;
;     u.pm = fm + ((wgid % nig) % gsz); u.pn = (wgid % nig) / gsz; u.kb = 0; u.kr = (kmode == 2) ? ((i & 1) ^ 1) : kmode; return true;
; template <class Epi, class Sched, bool ALIGN_EPI = true>
; __device__ __forceinline__ void gemm_phase(LAS unsigned char* lds, const Gemm g, const Sched& S, const Epi& E) {
;   const int tid = otid(), wid = __builtin_amdgcn_readfirstlane(tid >> 6), lane = tid & 63, wr = wid >> 2, wc = wid & 3, fr = lane & 15, fq = lane >> 4;
;   const int K = g.K, nt = K / BK;
;   unsigned voffA[2], voffB[2];
; #pragma unroll
;   for (int i = 0; i < 2; ++i) { int R, C; stage_rc(tid * 16 + i * 8192, R, C); const int Rb = Epi::PERM ? ((R & ~31) + perm32(R & 31)) : R;
;     voffA[i] = (unsigned)(R * g.lda + C) * 2u; voffB[i] = (unsigned)(Rb * g.ldb + C) * 2u; }
;   const size_t koffL = (size_t)(nt - 1) * (BK * 2);
;   const size_t hstepA = (size_t)HALF * g.lda * 2, hstepB = (size_t)HALF * g.ldb * 2;
;   const size_t tstepA = 2 * hstepA, tstepB = 2 * hstepB;
;   const unsigned ldsw = (unsigned)wid * 1024u;
;   const int aoff = lds_byte(wr * 64 + fr, fq * 8), boff = lds_byte(wc * 32 + fr, fq * 8);
;     ...
;   Unit cur, nxt; int ui = 0;
;   if (!S.next(0, cur)) return;
;   f32x4 acc[2][2][4][2];
; #pragma unroll
;   for (int a = 0; a < 2; ++a)
; #pragma unroll
;     for (int b = 0; b < 2; ++b)
; #pragma unroll
;       for (int m = 0; m < 4; ++m)
; #pragma unroll
;         for (int n = 0; n < 2; ++n) acc[a][b][m][n] = (f32x4){0.f, 0.f, 0.f, 0.f};
;   bf16x8 At[4][2], B0[2][2], B1[2][2];
;   ptrdiff_t kstep = cur.kr ? -(ptrdiff_t)(BK * 2) : (ptrdiff_t)(BK * 2);
;   const char* cA = (const char*)g.A + (size_t)cur.pm * tstepA + cur.kb + (cur.kr ? koffL : 0); const char* cB = (const char*)g.Bt + (size_t)cur.pn * tstepB + cur.kb + (cur.kr ? koffL : 0);
;   PG8_STAGE(PG8_SB(0, 0), cB, voffB); PG8_STAGE(PG8_SB(0, 1), cB + hstepB, voffB); PG8_STAGE(PG8_SA(0, 0), cA, voffA); PG8_STAGE(PG8_SA(0, 1), cA + hstepA, voffA);
;   if (wr == 1) PG8_BAR;
.LBB0_1665:
	v_bfe_i32 v3, v0, 27, 1
	v_lshlrev_b32_e32 v1, 4, v0
	v_lshrrev_b32_e32 v3, 22, v3
	v_add_u32_e32 v3, v1, v3
	v_and_b32_e32 v3, 0xfffffc00, v3
	v_sub_u32_e32 v3, v1, v3
	v_ashrrev_i32_e32 v2, 31, v0
	v_lshrrev_b32_e32 v4, 4, v3
	v_lshrrev_b32_e32 v2, 26, v2
	v_bitop3_b32 v4, v4, v3, 32 bitop3:0x6c
	v_ashrrev_i32_e32 v3, 31, v3
	v_add_u32_e32 v2, v0, v2
	v_lshrrev_b32_e32 v3, 26, v3
	v_ashrrev_i32_e32 v2, 6, v2
	v_add_u32_e32 v3, v4, v3
	v_lshlrev_b32_e32 v5, 3, v2
	v_ashrrev_i32_e32 v3, 6, v3
	v_and_b32_e32 v5, -16, v5
	v_mul_i32_i24_e32 v6, 64, v3
	v_add_u32_e32 v5, v3, v5
	v_sub_u32_e32 v4, v4, v6
	v_mov_b32_e32 v6, 1
	v_lshlrev_b32_e32 v2, 5, v2
	v_ashrrev_i16_sdwa v4, v6, sext(v4) dst_sel:DWORD dst_unused:UNUSED_PAD src0_sel:DWORD src1_sel:BYTE_0
	v_lshlrev_b32_e32 v7, 1, v5
	v_lshrrev_b32_e32 v8, 2, v5
	v_and_b32_e32 v3, 3, v3
	s_mov_b32 s3, 0x3ffe0
	s_add_u32 s1, s84, 0x7c00000
	v_and_b32_e32 v2, 32, v2
	v_bfe_i32 v4, v4, 0, 16
	v_and_b32_e32 v7, 24, v7
	v_and_b32_e32 v8, 4, v8
	v_and_or_b32 v3, v5, s3, v3
	s_addc_u32 s2, s85, 0
	v_or3_b32 v3, v3, v8, v7
	v_add_lshl_u32 v2, v2, v4, 1
	v_add_u32_e32 v1, 0x2000, v1
	s_add_i32 s4, s6, s4
	v_lshl_add_u32 v144, v5, 14, v2
	v_lshl_add_u32 v146, v3, 14, v2
	v_ashrrev_i32_e32 v2, 31, v1
	s_ashr_i32 s6, s4, 31
	v_lshrrev_b32_e32 v2, 22, v2
	s_lshr_b32 s6, s6, 26
	v_add_u32_e32 v2, v1, v2
	s_add_i32 s6, s4, s6
	v_ashrrev_i32_e32 v2, 10, v2
	s_ashr_i32 s7, s6, 6
	s_and_b32 s6, s6, 0xffc0
	v_mul_i32_i24_e32 v3, 0x400, v2
	s_sub_i32 s6, s4, s6
	v_sub_u32_e32 v1, v1, v3
	s_bfe_i32 s4, s6, 0x80000
	v_lshrrev_b32_e32 v3, 4, v1
	s_bfe_u32 s4, s4, 0x3000c
	v_bitop3_b32 v1, v3, v1, 32 bitop3:0x6c
	s_add_i32 s10, s6, s4
	v_ashrrev_i32_e32 v4, 31, v1
	s_bfe_i32 s4, s10, 0x80000
	s_and_b32 s10, s10, 0xf8
	v_lshrrev_b32_e32 v4, 26, v4
	s_sub_i32 s6, s6, s10
	v_lshlrev_b32_e32 v3, 3, v2
	v_add_u32_e32 v4, v1, v4
	s_lshl_b32 s7, s7, 3
	s_sext_i32_i16 s4, s4
	s_sext_i32_i8 s6, s6
	s_ashr_i32 s5, s8, 6
	v_and_b32_e32 v3, -16, v3
	v_ashrrev_i32_e32 v5, 6, v4
	s_lshr_b32 s4, s4, 3
	s_add_i32 s30, s7, s4
	s_mov_b32 s4, s6
	v_add_u32_e32 v3, v5, v3
	v_and_b32_e32 v5, 3, v5
	s_ashr_i32 s31, s30, 31
	s_bfe_i64 s[10:11], s[4:5], 0x100000
	v_and_or_b32 v5, v3, s3, v5
	s_ashr_i32 s9, s8, 8
	s_lshl_b32 s3, s5, 10
	s_lshl_b64 s[6:7], s[30:31], 22
	s_lshl_b64 s[10:11], s[10:11], 22
	s_add_u32 s10, s1, s10
	s_addc_u32 s11, s2, s11
	s_add_u32 s34, s10, 0x3f80
	v_and_b32_e32 v4, 0xc0, v4
	s_addc_u32 s35, s11, 0
	s_add_i32 s31, s3, 0
	v_sub_u32_e32 v1, v1, v4
	s_add_i32 m0, s31, 0x10000
	v_lshlrev_b32_e32 v2, 5, v2
	v_ashrrev_i16_sdwa v1, v6, sext(v1) dst_sel:DWORD dst_unused:UNUSED_PAD src0_sel:DWORD src1_sel:BYTE_0
	v_lshlrev_b32_e32 v4, 1, v3
	v_lshrrev_b32_e32 v6, 2, v3
	global_load_lds_dwordx4 v146, s[34:35]
	s_add_i32 m0, s31, 0x12000
	v_and_b32_e32 v2, 32, v2
	v_bfe_i32 v1, v1, 0, 16
	v_and_b32_e32 v4, 24, v4
	v_and_b32_e32 v6, 4, v6
	s_add_u32 s12, s92, s6
	v_or3_b32 v4, v5, v6, v4
	v_add_lshl_u32 v1, v2, v1, 1
	s_addc_u32 s13, s93, s7
	v_lshl_add_u32 v150, v4, 14, v1
	s_add_u32 s6, s10, 0x203f80
	global_load_lds_dwordx4 v150, s[34:35]
	s_addc_u32 s7, s11, 0
	s_add_i32 m0, s31, 0x14000
	v_lshl_add_u32 v148, v3, 14, v1
	global_load_lds_dwordx4 v146, s[6:7]
	s_add_i32 m0, s31, 0x16000
	s_add_u32 s36, s12, 0x3f80
	s_addc_u32 s37, s13, 0
	s_add_i32 s33, s31, 0x2000
	global_load_lds_dwordx4 v150, s[6:7]
	s_mov_b32 m0, s31
	s_add_u32 s6, s12, 0x203f80
	global_load_lds_dwordx4 v144, s[36:37]
	s_mov_b32 m0, s33
	s_addc_u32 s7, s13, 0
	s_add_i32 s54, s31, 0x4000
	global_load_lds_dwordx4 v148, s[36:37]
	s_mov_b32 m0, s54
	s_add_i32 s55, s31, 0x6000
	global_load_lds_dwordx4 v144, s[6:7]
	s_mov_b32 m0, s55
	v_mov_b32_e32 v147, 0
	global_load_lds_dwordx4 v148, s[6:7]
	s_cmp_eq_u32 s9, 1
	s_mov_b32 s56, 0
	v_mov_b32_e32 v151, v147
	v_mov_b32_e32 v145, v147
	s_cselect_b64 s[6:7], -1, 0
	s_cmp_lg_u32 s9, 1
	v_mov_b32_e32 v149, v147
	s_cbranch_scc1 .LBB0_1667
	s_barrier

;   __device__ bool next(int i, Unit& u) const {
;     const long L = (long)i * G + c; if (L >= nwg) return false;
;     int wgid = (int)L; { const int q = nwg / NXCD, r = nwg % NXCD, xcd = wgid % NXCD, off = wgid / NXCD; wgid = (xcd < r ? xcd * (q + 1) : r * (q + 1) + (xcd - r) * q) + off; }
;     const int nig = WGM * nN, gid = wgid / nig, fm = gid * WGM, gsz = (nM - fm) < WGM ? (nM - fm) : WGM;
;     u.pm = fm + ((wgid % nig) % gsz); u.pn = (wgid % nig) / gsz; u.kb = 0; u.kr = (kmode == 2) ? ((i & 1) ^ 1) : kmode; return true;
.LBB0_1675:
	s_ashr_i32 s18, s20, 3
	s_add_i32 s18, s22, s18
	s_ashr_i32 s19, s18, 31
	s_lshr_b32 s19, s19, 26
	s_add_i32 s19, s18, s19
	s_ashr_i32 s20, s19, 6
	s_lshl_b32 s20, s20, 3
	s_sub_i32 s21, 64, s20
	s_min_i32 s21, s21, 8
	s_abs_i32 s22, s21
	v_cvt_f32_u32_e32 v0, s22
	s_sub_i32 s24, 0, s22
	s_andn2_b32 s19, s19, 63
	s_sub_i32 s19, s18, s19
	v_rcp_iflag_f32_e32 v0, v0
	s_abs_i32 s18, s19
	s_xor_b32 s23, s19, s21
	s_ashr_i32 s23, s23, 31
	v_mul_f32_e32 v0, 0x4f7ffffe, v0
	v_cvt_u32_f32_e32 v0, v0
	s_nop 0
	v_readfirstlane_b32 s25, v0
	s_mul_i32 s24, s24, s25
	s_mul_hi_u32 s24, s25, s24
	s_add_i32 s25, s25, s24
	s_mul_hi_u32 s24, s18, s25
	s_mul_i32 s25, s24, s22
	s_sub_i32 s18, s18, s25
	s_add_i32 s26, s24, 1
	s_sub_i32 s25, s18, s22
	s_cmp_ge_u32 s18, s22
	s_cselect_b32 s24, s26, s24
	s_cselect_b32 s18, s25, s18
	s_add_i32 s25, s24, 1
	s_cmp_ge_u32 s18, s22
	s_cselect_b32 s18, s25, s24
	s_xor_b32 s18, s18, s23
	s_sub_i32 s18, s18, s23
	s_mul_i32 s21, s18, s21
	s_sub_i32 s19, s19, s21
	s_add_i32 s20, s20, s18
	s_mov_b32 s18, s19
	s_andn2_b32 s70, 1, s56
